# baseline (speedup 1.0000x reference)
.LBB0_97:
	v_readlane_b32 s4, v254, 53
	s_add_i32 s33, s4, s57
	s_cmpk_lt_i32 s33, 0x180
	s_mov_b64 s[4:5], -1
	s_cbranch_scc1 .LBB0_134
	v_readlane_b32 s4, v255, 4
	v_readlane_b32 s5, v255, 5
	s_andn2_b64 vcc, exec, s[4:5]
	s_cbranch_vccnz .LBB0_133
	s_mov_b32 s4, -1
	s_cmpk_gt_u32 s33, 0x62b
	v_mbcnt_lo_u32_b32 v0, s4, 0
	v_mbcnt_hi_u32_b32 v0, s4, v0
	v_add_u32_e32 v0, s43, v0
	s_cbranch_scc1 .LBB0_133
	v_ashrrev_i32_e32 v6, 4, v0
	v_and_b32_e32 v2, 15, v0
	v_lshlrev_b32_e32 v3, 2, v6
	v_and_b32_e32 v1, 12, v3
	v_bfe_i32 v4, v6, 2, 1
	s_movk_i32 s4, 0x1600
	v_and_or_b32 v4, v4, s4, v1
	v_lshlrev_b32_e32 v5, 7, v6
	s_movk_i32 s4, 0x200
	v_and_or_b32 v5, v5, s4, v1
	v_lshlrev_b32_e32 v0, 4, v2
	v_lshlrev_b32_e32 v2, 3, v2
	s_mov_b32 s36, s59
	s_branch .LBB0_103

.LBB0_102:
	s_and_b32 s10, 0xffff, s29
	v_lshl_add_u32 v1, s10, 7, v2
	v_lshl_add_u64 v[10:11], v[196:197], 2, s[8:9]
	v_mul_lo_u32 v12, v1, s37
	v_mov_b32_e32 v13, v197
	s_lshl_b32 s8, s37, 2
	s_mov_b32 s9, 0
	v_lshl_add_u64 v[12:13], v[12:13], 2, v[10:11]
	v_lshl_add_u64 v[14:15], v[12:13], 0, s[8:9]
	v_lshl_add_u64 v[16:17], v[14:15], 0, s[8:9]
	v_lshl_add_u64 v[18:19], v[16:17], 0, s[8:9]
	v_lshl_add_u64 v[20:21], v[18:19], 0, s[8:9]
	v_lshl_add_u64 v[22:23], v[20:21], 0, s[8:9]
	v_lshl_add_u64 v[24:25], v[22:23], 0, s[8:9]
	v_lshl_add_u64 v[26:27], v[24:25], 0, s[8:9]
	global_load_dwordx4 v[36:39], v[12:13], off
	global_load_dwordx4 v[40:43], v[14:15], off
	global_load_dwordx4 v[44:47], v[16:17], off
	global_load_dwordx4 v[48:51], v[18:19], off
	global_load_dwordx4 v[52:55], v[20:21], off
	global_load_dwordx4 v[56:59], v[22:23], off
	global_load_dwordx4 v[60:63], v[24:25], off
	global_load_dwordx4 v[64:67], v[26:27], off
	s_lshl_b32 s8, s10, 8
	s_add_u32 s6, s6, s8
	s_addc_u32 s7, s7, 0
	v_lshl_add_u32 v35, v6, 2, s28
	v_mov_b32_e32 v1, v197
	v_lshl_add_u64 v[14:15], s[6:7], 0, v[0:1]
	v_mul_lo_u32 v32, v35, s4
	v_mov_b32_e32 v33, v197
	s_lshl_b32 s6, s4, 1
	s_mov_b32 s7, 0
	v_lshl_add_u64 v[32:33], v[32:33], 1, v[14:15]
	v_lshl_add_u64 v[34:35], v[32:33], 0, s[6:7]
	v_lshl_add_u64 v[12:13], v[34:35], 0, s[6:7]
	v_lshl_add_u64 v[10:11], v[12:13], 0, s[6:7]
	s_add_i32 s36, s36, s58
	s_cmpk_gt_i32 s36, 0x1fff
	s_waitcnt vmcnt(0)
	v_cvt_pk_bf16_f32 v16, v36, v40
	v_cvt_pk_bf16_f32 v17, v44, v48
	v_cvt_pk_bf16_f32 v18, v52, v56
	v_cvt_pk_bf16_f32 v19, v60, v64
	v_cvt_pk_bf16_f32 v20, v37, v41
	v_cvt_pk_bf16_f32 v21, v45, v49
	v_cvt_pk_bf16_f32 v22, v53, v57
	v_cvt_pk_bf16_f32 v23, v61, v65
	v_cvt_pk_bf16_f32 v24, v38, v42
	v_cvt_pk_bf16_f32 v25, v46, v50
	v_cvt_pk_bf16_f32 v26, v54, v58
	v_cvt_pk_bf16_f32 v27, v62, v66
	v_cvt_pk_bf16_f32 v28, v39, v43
	v_cvt_pk_bf16_f32 v29, v47, v51
	v_cvt_pk_bf16_f32 v30, v55, v59
	v_cvt_pk_bf16_f32 v31, v63, v67
	global_store_dwordx4 v[32:33], v[16:19], off
	global_store_dwordx4 v[34:35], v[20:23], off
	global_store_dwordx4 v[12:13], v[24:27], off
	global_store_dwordx4 v[10:11], v[28:31], off
	s_cbranch_scc1 .LBB0_132

.LBB0_146:
	v_readlane_b32 s6, v254, 53
	s_add_i32 s64, s6, s61
	s_cmpk_lt_i32 s64, 0x840
	s_mov_b64 s[6:7], -1
	s_cbranch_scc1 .LBB0_182
	v_readlane_b32 s6, v255, 4
	v_readlane_b32 s7, v255, 5
	s_andn2_b64 vcc, exec, s[6:7]
	s_cbranch_vccnz .LBB0_181
	s_mov_b32 s6, -1
	s_cmpk_gt_u32 s64, 0xe1b
	v_mbcnt_lo_u32_b32 v0, s6, 0
	v_mbcnt_hi_u32_b32 v0, s6, v0
	v_add_u32_e32 v0, s43, v0
	s_cbranch_scc1 .LBB0_181
	v_ashrrev_i32_e32 v6, 4, v0
	v_and_b32_e32 v2, 15, v0
	v_lshlrev_b32_e32 v3, 2, v6
	v_and_b32_e32 v1, 12, v3
	v_bfe_i32 v4, v6, 2, 1
	s_movk_i32 s6, 0x1600
	v_and_or_b32 v4, v4, s6, v1
	v_lshlrev_b32_e32 v5, 7, v6
	s_movk_i32 s6, 0x200
	v_and_or_b32 v5, v5, s6, v1
	v_lshlrev_b32_e32 v0, 4, v2
	v_lshlrev_b32_e32 v2, 3, v2
	s_mov_b32 s33, s63
	s_branch .LBB0_152

.LBB0_151:
	s_and_b32 s28, 0xffff, s40
	v_lshl_add_u32 v1, s28, 7, v2
	v_lshl_add_u64 v[10:11], v[196:197], 2, s[10:11]
	v_mul_lo_u32 v12, v1, s37
	v_mov_b32_e32 v13, v197
	s_lshl_b32 s10, s37, 2
	s_mov_b32 s11, 0
	v_lshl_add_u64 v[12:13], v[12:13], 2, v[10:11]
	v_lshl_add_u64 v[14:15], v[12:13], 0, s[10:11]
	v_lshl_add_u64 v[16:17], v[14:15], 0, s[10:11]
	v_lshl_add_u64 v[18:19], v[16:17], 0, s[10:11]
	v_lshl_add_u64 v[20:21], v[18:19], 0, s[10:11]
	v_lshl_add_u64 v[22:23], v[20:21], 0, s[10:11]
	v_lshl_add_u64 v[24:25], v[22:23], 0, s[10:11]
	v_lshl_add_u64 v[26:27], v[24:25], 0, s[10:11]
	global_load_dwordx4 v[36:39], v[12:13], off
	global_load_dwordx4 v[40:43], v[14:15], off
	global_load_dwordx4 v[44:47], v[16:17], off
	global_load_dwordx4 v[48:51], v[18:19], off
	global_load_dwordx4 v[52:55], v[20:21], off
	global_load_dwordx4 v[56:59], v[22:23], off
	global_load_dwordx4 v[60:63], v[24:25], off
	global_load_dwordx4 v[64:67], v[26:27], off
	s_lshl_b32 s10, s28, 8
	s_add_u32 s8, s8, s10
	s_addc_u32 s9, s9, 0
	v_lshl_add_u32 v35, v6, 2, s36
	v_mov_b32_e32 v1, v197
	v_lshl_add_u64 v[14:15], s[8:9], 0, v[0:1]
	v_mul_lo_u32 v32, v35, s6
	v_mov_b32_e32 v33, v197
	s_lshl_b32 s8, s6, 1
	s_mov_b32 s9, 0
	v_lshl_add_u64 v[32:33], v[32:33], 1, v[14:15]
	v_lshl_add_u64 v[34:35], v[32:33], 0, s[8:9]
	v_lshl_add_u64 v[12:13], v[34:35], 0, s[8:9]
	v_lshl_add_u64 v[10:11], v[12:13], 0, s[8:9]
	s_add_i32 s33, s33, s62
	s_cmpk_gt_i32 s33, 0x1b53
	v_readlane_b32 s40, v254, 59
	s_waitcnt vmcnt(0)
	v_cvt_pk_bf16_f32 v16, v36, v40
	v_cvt_pk_bf16_f32 v17, v44, v48
	v_cvt_pk_bf16_f32 v18, v52, v56
	v_cvt_pk_bf16_f32 v19, v60, v64
	v_cvt_pk_bf16_f32 v20, v37, v41
	v_cvt_pk_bf16_f32 v21, v45, v49
	v_cvt_pk_bf16_f32 v22, v53, v57
	v_cvt_pk_bf16_f32 v23, v61, v65
	v_cvt_pk_bf16_f32 v24, v38, v42
	v_cvt_pk_bf16_f32 v25, v46, v50
	v_cvt_pk_bf16_f32 v26, v54, v58
	v_cvt_pk_bf16_f32 v27, v62, v66
	v_cvt_pk_bf16_f32 v28, v39, v43
	v_cvt_pk_bf16_f32 v29, v47, v51
	v_cvt_pk_bf16_f32 v30, v55, v59
	v_cvt_pk_bf16_f32 v31, v63, v67
	global_store_dwordx4 v[32:33], v[16:19], off
	global_store_dwordx4 v[34:35], v[20:23], off
	global_store_dwordx4 v[12:13], v[24:27], off
	global_store_dwordx4 v[10:11], v[28:31], off
	s_cbranch_scc1 .LBB0_181

.LBB0_214:
	v_readlane_b32 s6, v254, 53
	s_add_i32 s33, s6, s55
	s_cmpk_lt_i32 s33, 0x180
	s_mov_b64 s[6:7], -1
	s_cbranch_scc1 .LBB0_251
	v_readlane_b32 s6, v255, 4
	v_readlane_b32 s7, v255, 5
	s_andn2_b64 vcc, exec, s[6:7]
	s_cbranch_vccnz .LBB0_250
	s_mov_b32 s6, -1
	s_cmpk_gt_u32 s33, 0x49f
	v_mbcnt_lo_u32_b32 v0, s6, 0
	v_mbcnt_hi_u32_b32 v0, s6, v0
	v_add_u32_e32 v0, s43, v0
	s_cbranch_scc1 .LBB0_250
	v_ashrrev_i32_e32 v6, 4, v0
	v_and_b32_e32 v2, 15, v0
	v_lshlrev_b32_e32 v3, 2, v6
	v_and_b32_e32 v1, 12, v3
	v_bfe_i32 v4, v6, 2, 1
	s_movk_i32 s6, 0x1600
	v_and_or_b32 v4, v4, s6, v1
	v_lshlrev_b32_e32 v5, 7, v6
	s_movk_i32 s6, 0x200
	v_and_or_b32 v5, v5, s6, v1
	v_lshlrev_b32_e32 v0, 4, v2
	v_lshlrev_b32_e32 v2, 3, v2
	s_mov_b32 s36, s77
	s_branch .LBB0_220

.LBB0_219:
	s_and_b32 s28, 0xffff, s41
	v_lshl_add_u32 v1, s28, 7, v2
	v_lshl_add_u64 v[10:11], v[196:197], 2, s[10:11]
	v_mul_lo_u32 v12, v1, s38
	v_mov_b32_e32 v13, v197
	s_lshl_b32 s10, s38, 2
	s_mov_b32 s11, 0
	v_lshl_add_u64 v[12:13], v[12:13], 2, v[10:11]
	v_lshl_add_u64 v[14:15], v[12:13], 0, s[10:11]
	v_lshl_add_u64 v[16:17], v[14:15], 0, s[10:11]
	v_lshl_add_u64 v[18:19], v[16:17], 0, s[10:11]
	v_lshl_add_u64 v[20:21], v[18:19], 0, s[10:11]
	v_lshl_add_u64 v[22:23], v[20:21], 0, s[10:11]
	v_lshl_add_u64 v[24:25], v[22:23], 0, s[10:11]
	v_lshl_add_u64 v[26:27], v[24:25], 0, s[10:11]
	global_load_dwordx4 v[36:39], v[12:13], off
	global_load_dwordx4 v[40:43], v[14:15], off
	global_load_dwordx4 v[44:47], v[16:17], off
	global_load_dwordx4 v[48:51], v[18:19], off
	global_load_dwordx4 v[52:55], v[20:21], off
	global_load_dwordx4 v[56:59], v[22:23], off
	global_load_dwordx4 v[60:63], v[24:25], off
	global_load_dwordx4 v[64:67], v[26:27], off
	s_lshl_b32 s10, s28, 8
	s_add_u32 s8, s8, s10
	s_addc_u32 s9, s9, 0
	v_lshl_add_u32 v35, v6, 2, s37
	v_mov_b32_e32 v1, v197
	v_lshl_add_u64 v[14:15], s[8:9], 0, v[0:1]
	v_mul_lo_u32 v32, v35, s6
	v_mov_b32_e32 v33, v197
	s_lshl_b32 s8, s6, 1
	s_mov_b32 s9, 0
	v_lshl_add_u64 v[32:33], v[32:33], 1, v[14:15]
	v_lshl_add_u64 v[34:35], v[32:33], 0, s[8:9]
	v_lshl_add_u64 v[12:13], v[34:35], 0, s[8:9]
	v_lshl_add_u64 v[10:11], v[12:13], 0, s[8:9]
	s_add_i32 s36, s36, s76
	s_cmpk_gt_i32 s36, 0x1577
	s_waitcnt vmcnt(0)
	v_cvt_pk_bf16_f32 v16, v36, v40
	v_cvt_pk_bf16_f32 v17, v44, v48
	v_cvt_pk_bf16_f32 v18, v52, v56
	v_cvt_pk_bf16_f32 v19, v60, v64
	v_cvt_pk_bf16_f32 v20, v37, v41
	v_cvt_pk_bf16_f32 v21, v45, v49
	v_cvt_pk_bf16_f32 v22, v53, v57
	v_cvt_pk_bf16_f32 v23, v61, v65
	v_cvt_pk_bf16_f32 v24, v38, v42
	v_cvt_pk_bf16_f32 v25, v46, v50
	v_cvt_pk_bf16_f32 v26, v54, v58
	v_cvt_pk_bf16_f32 v27, v62, v66
	v_cvt_pk_bf16_f32 v28, v39, v43
	v_cvt_pk_bf16_f32 v29, v47, v51
	v_cvt_pk_bf16_f32 v30, v55, v59
	v_cvt_pk_bf16_f32 v31, v63, v67
	global_store_dwordx4 v[32:33], v[16:19], off
	global_store_dwordx4 v[34:35], v[20:23], off
	global_store_dwordx4 v[12:13], v[24:27], off
	global_store_dwordx4 v[10:11], v[28:31], off
	s_cbranch_scc1 .LBB0_249

.LBB0_266:
	v_readlane_b32 s4, v254, 53
	s_add_i32 s10, s4, s54
	s_cmpk_lt_i32 s10, 0x180
	s_mov_b64 s[4:5], -1
	s_cbranch_scc1 .LBB0_302
	v_readlane_b32 s4, v255, 4
	v_readlane_b32 s5, v255, 5
	s_andn2_b64 vcc, exec, s[4:5]
	s_cbranch_vccnz .LBB0_301
	s_mov_b32 s4, -1
	s_cmpk_gt_u32 s10, 0x697
	v_mbcnt_lo_u32_b32 v160, s4, 0
	v_mbcnt_hi_u32_b32 v160, s4, v160
	v_add_u32_e32 v160, s43, v160
	s_cbranch_scc1 .LBB0_301
	v_ashrrev_i32_e32 v166, 4, v160
	v_and_b32_e32 v162, 15, v160
	v_lshlrev_b32_e32 v163, 2, v166
	v_and_b32_e32 v161, 12, v163
	v_bfe_i32 v164, v166, 2, 1
	s_movk_i32 s4, 0x1600
	v_and_or_b32 v164, v164, s4, v161
	v_lshlrev_b32_e32 v165, 7, v166
	s_movk_i32 s4, 0x200
	v_and_or_b32 v165, v165, s4, v161
	v_lshlrev_b32_e32 v160, 4, v162
	v_lshlrev_b32_e32 v162, 3, v162
	s_mov_b32 s11, s39
	s_branch .LBB0_272

.LBB0_271:
	s_and_b32 s28, 0xffff, s38
	v_lshl_add_u32 v161, s28, 7, v162
	v_lshl_add_u64 v[170:171], v[196:197], 2, s[8:9]
	v_mul_lo_u32 v172, v161, s34
	v_mov_b32_e32 v173, v197
	s_lshl_b32 s8, s34, 2
	s_mov_b32 s9, 0
	v_lshl_add_u64 v[172:173], v[172:173], 2, v[170:171]
	v_lshl_add_u64 v[174:175], v[172:173], 0, s[8:9]
	v_lshl_add_u64 v[176:177], v[174:175], 0, s[8:9]
	v_lshl_add_u64 v[178:179], v[176:177], 0, s[8:9]
	v_lshl_add_u64 v[180:181], v[178:179], 0, s[8:9]
	v_lshl_add_u64 v[182:183], v[180:181], 0, s[8:9]
	v_lshl_add_u64 v[184:185], v[182:183], 0, s[8:9]
	v_lshl_add_u64 v[186:187], v[184:185], 0, s[8:9]
	global_load_dwordx4 v[204:207], v[172:173], off
	global_load_dwordx4 v[208:211], v[174:175], off
	global_load_dwordx4 v[212:215], v[176:177], off
	global_load_dwordx4 v[216:219], v[178:179], off
	global_load_dwordx4 v[220:223], v[180:181], off
	global_load_dwordx4 v[228:231], v[182:183], off
	global_load_dwordx4 v[232:235], v[184:185], off
	global_load_dwordx4 v[236:239], v[186:187], off
	s_lshl_b32 s8, s28, 8
	s_add_u32 s6, s6, s8
	s_addc_u32 s7, s7, 0
	v_lshl_add_u32 v195, v166, 2, s33
	v_mov_b32_e32 v161, v197
	v_lshl_add_u64 v[174:175], s[6:7], 0, v[160:161]
	v_mul_lo_u32 v192, v195, s4
	v_mov_b32_e32 v193, v197
	s_lshl_b32 s6, s4, 1
	s_mov_b32 s7, 0
	v_lshl_add_u64 v[192:193], v[192:193], 1, v[174:175]
	v_lshl_add_u64 v[194:195], v[192:193], 0, s[6:7]
	v_lshl_add_u64 v[172:173], v[194:195], 0, s[6:7]
	v_lshl_add_u64 v[170:171], v[172:173], 0, s[6:7]
	s_add_i32 s11, s11, s55
	s_cmpk_gt_i32 s11, 0x1257
	s_waitcnt vmcnt(0)
	v_cvt_pk_bf16_f32 v176, v204, v208
	v_cvt_pk_bf16_f32 v177, v212, v216
	v_cvt_pk_bf16_f32 v178, v220, v228
	v_cvt_pk_bf16_f32 v179, v232, v236
	v_cvt_pk_bf16_f32 v180, v205, v209
	v_cvt_pk_bf16_f32 v181, v213, v217
	v_cvt_pk_bf16_f32 v182, v221, v229
	v_cvt_pk_bf16_f32 v183, v233, v237
	v_cvt_pk_bf16_f32 v184, v206, v210
	v_cvt_pk_bf16_f32 v185, v214, v218
	v_cvt_pk_bf16_f32 v186, v222, v230
	v_cvt_pk_bf16_f32 v187, v234, v238
	v_cvt_pk_bf16_f32 v188, v207, v211
	v_cvt_pk_bf16_f32 v189, v215, v219
	v_cvt_pk_bf16_f32 v190, v223, v231
	v_cvt_pk_bf16_f32 v191, v235, v239
	global_store_dwordx4 v[192:193], v[176:179], off
	global_store_dwordx4 v[194:195], v[180:183], off
	global_store_dwordx4 v[172:173], v[184:187], off
	global_store_dwordx4 v[170:171], v[188:191], off
	s_cbranch_scc1 .LBB0_301

.LBB0_522:
	v_readlane_b32 s4, v254, 53
	s_add_i32 s34, s4, s62
	s_cmpk_lt_i32 s34, 0x8a0
	s_mov_b64 s[4:5], -1
	s_cbranch_scc1 .LBB0_558
	v_readlane_b32 s4, v255, 4
	v_readlane_b32 s5, v255, 5
	s_andn2_b64 vcc, exec, s[4:5]
	s_cbranch_vccnz .LBB0_557
	s_mov_b32 s4, -1
	s_nop 0
	v_mbcnt_lo_u32_b32 v0, s4, 0
	v_mbcnt_hi_u32_b32 v0, s4, v0
	s_add_i32 s4, s34, 0xffffff20
	v_add_u32_e32 v0, s43, v0
	s_cmpk_gt_u32 s4, 0xd3f
	s_cbranch_scc1 .LBB0_557
	v_ashrrev_i32_e32 v6, 4, v0
	v_and_b32_e32 v2, 15, v0
	v_lshlrev_b32_e32 v3, 2, v6
	v_and_b32_e32 v1, 12, v3
	v_bfe_i32 v4, v6, 2, 1
	s_movk_i32 s4, 0x1600
	v_and_or_b32 v4, v4, s4, v1
	v_lshlrev_b32_e32 v5, 7, v6
	s_movk_i32 s4, 0x200
	v_and_or_b32 v5, v5, s4, v1
	v_lshlrev_b32_e32 v0, 4, v2
	v_lshlrev_b32_e32 v2, 3, v2
	s_mov_b32 s33, s64
	s_branch .LBB0_528

.LBB0_527:
	s_and_b32 s10, 0xffff, s29
	v_lshl_add_u32 v1, s10, 7, v2
	v_lshl_add_u64 v[10:11], v[196:197], 2, s[8:9]
	v_mul_lo_u32 v12, v1, s36
	v_mov_b32_e32 v13, v197
	s_lshl_b32 s8, s36, 2
	s_mov_b32 s9, 0
	v_lshl_add_u64 v[12:13], v[12:13], 2, v[10:11]
	v_lshl_add_u64 v[14:15], v[12:13], 0, s[8:9]
	v_lshl_add_u64 v[16:17], v[14:15], 0, s[8:9]
	v_lshl_add_u64 v[18:19], v[16:17], 0, s[8:9]
	v_lshl_add_u64 v[20:21], v[18:19], 0, s[8:9]
	v_lshl_add_u64 v[22:23], v[20:21], 0, s[8:9]
	v_lshl_add_u64 v[24:25], v[22:23], 0, s[8:9]
	v_lshl_add_u64 v[26:27], v[24:25], 0, s[8:9]
	global_load_dwordx4 v[36:39], v[12:13], off
	global_load_dwordx4 v[40:43], v[14:15], off
	global_load_dwordx4 v[44:47], v[16:17], off
	global_load_dwordx4 v[48:51], v[18:19], off
	global_load_dwordx4 v[52:55], v[20:21], off
	global_load_dwordx4 v[56:59], v[22:23], off
	global_load_dwordx4 v[60:63], v[24:25], off
	global_load_dwordx4 v[64:67], v[26:27], off
	s_lshl_b32 s8, s10, 8
	s_add_u32 s6, s6, s8
	s_addc_u32 s7, s7, 0
	v_lshl_add_u32 v35, v6, 2, s28
	v_mov_b32_e32 v1, v197
	v_lshl_add_u64 v[14:15], s[6:7], 0, v[0:1]
	v_mul_lo_u32 v32, v35, s4
	v_mov_b32_e32 v33, v197
	s_lshl_b32 s6, s4, 1
	s_mov_b32 s7, 0
	v_lshl_add_u64 v[32:33], v[32:33], 1, v[14:15]
	v_lshl_add_u64 v[34:35], v[32:33], 0, s[6:7]
	v_lshl_add_u64 v[12:13], v[34:35], 0, s[6:7]
	v_lshl_add_u64 v[10:11], v[12:13], 0, s[6:7]
	s_add_i32 s33, s33, s63
	s_cmpk_gt_i32 s33, 0xd3f
	s_waitcnt vmcnt(0)
	v_cvt_pk_bf16_f32 v16, v36, v40
	v_cvt_pk_bf16_f32 v17, v44, v48
	v_cvt_pk_bf16_f32 v18, v52, v56
	v_cvt_pk_bf16_f32 v19, v60, v64
	v_cvt_pk_bf16_f32 v20, v37, v41
	v_cvt_pk_bf16_f32 v21, v45, v49
	v_cvt_pk_bf16_f32 v22, v53, v57
	v_cvt_pk_bf16_f32 v23, v61, v65
	v_cvt_pk_bf16_f32 v24, v38, v42
	v_cvt_pk_bf16_f32 v25, v46, v50
	v_cvt_pk_bf16_f32 v26, v54, v58
	v_cvt_pk_bf16_f32 v27, v62, v66
	v_cvt_pk_bf16_f32 v28, v39, v43
	v_cvt_pk_bf16_f32 v29, v47, v51
	v_cvt_pk_bf16_f32 v30, v55, v59
	v_cvt_pk_bf16_f32 v31, v63, v67
	global_store_dwordx4 v[32:33], v[16:19], off
	global_store_dwordx4 v[34:35], v[20:23], off
	global_store_dwordx4 v[12:13], v[24:27], off
	global_store_dwordx4 v[10:11], v[28:31], off
	s_cbranch_scc1 .LBB0_557

.LBB0_892:
	s_or_b64 exec, exec, s[10:11]
	v_readlane_b32 s4, v254, 1
	v_readlane_b32 s5, v254, 2
	s_andn2_b64 vcc, exec, s[4:5]
	s_cbranch_vccnz .LBB0_21
	v_ashrrev_i32_e32 v6, 4, v40
	v_and_b32_e32 v2, 15, v40
	v_lshlrev_b32_e32 v3, 2, v6
	v_and_b32_e32 v1, 12, v3
	v_bfe_i32 v4, v6, 2, 1
	s_movk_i32 s4, 0x1600
	v_and_or_b32 v4, v4, s4, v1
	v_lshlrev_b32_e32 v5, 7, v6
	s_movk_i32 s4, 0x200
	v_and_or_b32 v5, v5, s4, v1
	v_lshlrev_b32_e32 v0, 4, v2
	v_lshlrev_b32_e32 v2, 3, v2
	v_readlane_b32 s33, v253, 0
	s_branch .LBB0_896

.LBB0_895:
	s_and_b32 s10, 0xffff, s29
	v_lshl_add_u32 v1, s10, 7, v2
	v_lshl_add_u64 v[10:11], v[196:197], 2, s[8:9]
	v_mul_lo_u32 v12, v1, s34
	v_mov_b32_e32 v13, v197
	s_lshl_b32 s8, s34, 2
	s_mov_b32 s9, 0
	v_lshl_add_u64 v[12:13], v[12:13], 2, v[10:11]
	v_lshl_add_u64 v[14:15], v[12:13], 0, s[8:9]
	v_lshl_add_u64 v[16:17], v[14:15], 0, s[8:9]
	v_lshl_add_u64 v[18:19], v[16:17], 0, s[8:9]
	v_lshl_add_u64 v[20:21], v[18:19], 0, s[8:9]
	v_lshl_add_u64 v[22:23], v[20:21], 0, s[8:9]
	v_lshl_add_u64 v[24:25], v[22:23], 0, s[8:9]
	v_lshl_add_u64 v[26:27], v[24:25], 0, s[8:9]
	global_load_dwordx4 v[36:39], v[12:13], off
	global_load_dwordx4 v[40:43], v[14:15], off
	global_load_dwordx4 v[44:47], v[16:17], off
	global_load_dwordx4 v[48:51], v[18:19], off
	global_load_dwordx4 v[52:55], v[20:21], off
	global_load_dwordx4 v[56:59], v[22:23], off
	global_load_dwordx4 v[60:63], v[24:25], off
	global_load_dwordx4 v[64:67], v[26:27], off
	s_lshl_b32 s8, s10, 8
	s_add_u32 s6, s6, s8
	s_addc_u32 s7, s7, 0
	v_lshl_add_u32 v35, v6, 2, s28
	v_mov_b32_e32 v1, v197
	v_lshl_add_u64 v[14:15], s[6:7], 0, v[0:1]
	v_mul_lo_u32 v32, v35, s4
	v_mov_b32_e32 v33, v197
	s_lshl_b32 s6, s4, 1
	s_mov_b32 s7, 0
	v_lshl_add_u64 v[32:33], v[32:33], 1, v[14:15]
	v_lshl_add_u64 v[34:35], v[32:33], 0, s[6:7]
	v_lshl_add_u64 v[12:13], v[34:35], 0, s[6:7]
	v_lshl_add_u64 v[10:11], v[12:13], 0, s[6:7]
	s_add_i32 s33, s33, s42
	s_cmpk_gt_i32 s33, 0x7bf
	s_waitcnt vmcnt(0)
	v_cvt_pk_bf16_f32 v16, v36, v40
	v_cvt_pk_bf16_f32 v17, v44, v48
	v_cvt_pk_bf16_f32 v18, v52, v56
	v_cvt_pk_bf16_f32 v19, v60, v64
	v_cvt_pk_bf16_f32 v20, v37, v41
	v_cvt_pk_bf16_f32 v21, v45, v49
	v_cvt_pk_bf16_f32 v22, v53, v57
	v_cvt_pk_bf16_f32 v23, v61, v65
	v_cvt_pk_bf16_f32 v24, v38, v42
	v_cvt_pk_bf16_f32 v25, v46, v50
	v_cvt_pk_bf16_f32 v26, v54, v58
	v_cvt_pk_bf16_f32 v27, v62, v66
	v_cvt_pk_bf16_f32 v28, v39, v43
	v_cvt_pk_bf16_f32 v29, v47, v51
	v_cvt_pk_bf16_f32 v30, v55, v59
	v_cvt_pk_bf16_f32 v31, v63, v67
	global_store_dwordx4 v[32:33], v[16:19], off
	global_store_dwordx4 v[34:35], v[20:23], off
	global_store_dwordx4 v[12:13], v[24:27], off
	global_store_dwordx4 v[10:11], v[28:31], off
	s_cbranch_scc1 .LBB0_21
